# GEMM phase prologue: all seven start-up tile stages issued before the first wait (second group no longer waits behind the first)
# speedup vs baseline: 1.0071x; 1.0071x over previous
; #define PG8_STAGE(bufoff, gbase, voff) do { _Pragma("unroll") for (int _i = 0; _i < 2; ++_i) \
;         __builtin_amdgcn_global_load_lds((const unsigned*)((const char*)(gbase) + (voff)[_i]), (LAS unsigned*)(lds + (bufoff) + ldsw + _i * 8192), 16, 0, 0); } while (0)
; #define PG8_WAIT_V(n) asm volatile("s_waitcnt vmcnt(" #n ")" ::: "memory")
; #define PG8_BAR __builtin_amdgcn_s_barrier()
; template <bool F16, class Sched, class Epi>
; __device__ __forceinline__ void gemm_phase(LAS unsigned char* lds, const Gemm g, const Sched& S, const Epi& E, int wave_s) {
;     ...
;     const char* cA = (const char*)g.A + PG8_AOFF(cur); const char* cB = (const char*)g.Bt + (size_t)cur.pn * tstepB;
;     PG8_STAGE(PG8_SB(0, 0), cB, voffB); PG8_STAGE(PG8_SB(0, 1), cB + hstepB, voffB); PG8_STAGE(PG8_SA(0, 0), cA, voffA); PG8_STAGE(PG8_SA(0, 1), cA + hstepA, voffA);
;     if (wr == 1) PG8_BAR;
;     PG8_WAIT_V(2); PG8_BAR;
;     PG8_STAGE(PG8_SB(1, 0), cB + kstep, voffB); PG8_STAGE(PG8_SA(1, 0), cA + kstep, voffA); PG8_STAGE(PG8_SB(1, 1), cB + hstepB + kstep, voffB);
;     PG8_WAIT_V(6); PG8_BAR;
.LBB0_226:
	s_add_u32 s6, s2, 0x24100000
	s_addc_u32 s7, s3, 0
	s_lshl_b64 s[8:9], s[18:19], 2
	s_add_u32 s2, s2, s8
	s_addc_u32 s3, s3, s9
	s_add_u32 s8, s2, 0x24008000
	s_addc_u32 s9, s3, 0
	v_bfe_u32 v15, v14, 4, 2
	s_lshl_b32 s0, s0, 5
	v_and_b32_e32 v16, 15, v14
	v_lshlrev_b32_e32 v17, 4, v15
	v_lshlrev_b32_e32 v14, 2, v14
	s_and_b32 s12, s0, 0x60
	s_add_i32 m0, s41, 0x18000
	v_lshl_add_u64 v[6:7], v[6:7], 0, s[54:55]
	v_lshl_or_b32 v162, s1, 6, v16
	v_lshl_or_b32 v16, v16, 6, v17
	s_lshl_b32 s1, s1, 13
	v_and_b32_e32 v14, 32, v14
	s_lshl_b32 s0, s12, 7
	global_load_lds_dwordx4 v[6:7], off
	v_lshl_add_u64 v[4:5], v[4:5], 0, s[54:55]
	s_add_i32 m0, s41, 0x1a000
	s_add_i32 s19, s41, 0x8000
	s_add_i32 s45, s41, 0xa000
	v_bitop3_b32 v163, v16, s0, v14 bitop3:0xde
	global_load_lds_dwordx4 v[4:5], off
	v_lshl_add_u64 v[0:1], v[0:1], 0, s[54:55]
	s_mov_b32 m0, s19
	s_add_u32 s0, s28, 0x20080
	v_bitop3_b32 v17, v16, s1, v14 bitop3:0xde
	global_load_lds_dwordx4 v[0:1], off
	v_lshl_add_u64 v[0:1], v[2:3], 0, s[54:55]
	s_mov_b32 m0, s45
	s_addc_u32 s1, s29, 0
	global_load_lds_dwordx4 v[0:1], off
	s_add_i32 m0, s41, 0x1c000
	v_lshl_add_u64 v[0:1], s[0:1], 0, v[176:177]
	global_load_lds_dwordx4 v[0:1], off
	v_lshl_add_u64 v[0:1], s[0:1], 0, v[128:129]
	s_add_i32 m0, s41, 0x1e000
	global_load_lds_dwordx4 v[0:1], off
	s_waitcnt vmcnt(8)
	s_barrier
	s_cmpk_lt_u32 s10, 0x100
	v_lshlrev_b32_e32 v0, 15, v11
	v_and_b32_e32 v0, 0xffff0000, v0
	v_lshl_add_u32 v0, v12, 12, v0
	v_and_b32_e32 v1, 1, v11
	v_lshl_or_b32 v0, v1, 6, v0
	v_lshl_add_u32 v134, v13, 1, v0
	v_lshlrev_b32_e32 v0, 15, v8
	v_and_b32_e32 v0, 0xffff0000, v0
	s_waitcnt vmcnt(6)
	v_lshl_add_u32 v0, v9, 12, v0
	v_and_b32_e32 v1, 1, v8
	v_lshl_or_b32 v0, v1, 6, v0
	s_cselect_b64 s[10:11], -1, 0
	s_mov_b32 s46, 0
	v_cmp_eq_u32_e64 s[2:3], 0, v15
	v_lshl_or_b32 v164, v15, 3, s12
	v_mov_b32_e32 v135, v177
	v_lshl_add_u32 v136, v10, 1, v0
	v_mov_b32_e32 v137, v177
	v_add_u32_e32 v165, 0, v17
	s_barrier
	s_branch .LBB0_229

; #define PG8_STAGE(bufoff, gbase, voff) do { _Pragma("unroll") for (int _i = 0; _i < 2; ++_i) \
;         __builtin_amdgcn_global_load_lds((const unsigned*)((const char*)(gbase) + (voff)[_i]), (LAS unsigned*)(lds + (bufoff) + ldsw + _i * 8192), 16, 0, 0); } while (0)
; #define PG8_WAIT_V(n) asm volatile("s_waitcnt vmcnt(" #n ")" ::: "memory")
; #define PG8_BAR __builtin_amdgcn_s_barrier()
; template <bool F16, class Sched, class Epi>
; __device__ __forceinline__ void gemm_phase(LAS unsigned char* lds, const Gemm g, const Sched& S, const Epi& E, int wave_s) {
;     ...
;     const char* cA = (const char*)g.A + PG8_AOFF(cur); const char* cB = (const char*)g.Bt + (size_t)cur.pn * tstepB;
;     PG8_STAGE(PG8_SB(0, 0), cB, voffB); PG8_STAGE(PG8_SB(0, 1), cB + hstepB, voffB); PG8_STAGE(PG8_SA(0, 0), cA, voffA); PG8_STAGE(PG8_SA(0, 1), cA + hstepA, voffA);
;     if (wr == 1) PG8_BAR;
;     PG8_WAIT_V(2); PG8_BAR;
;     PG8_STAGE(PG8_SB(1, 0), cB + kstep, voffB); PG8_STAGE(PG8_SA(1, 0), cA + kstep, voffA); PG8_STAGE(PG8_SB(1, 1), cB + hstepB + kstep, voffB);
;     PG8_WAIT_V(6); PG8_BAR;
.LBB0_300:
	s_add_u32 s14, s2, 0x1a000000
	s_addc_u32 s15, s3, 0
	s_lshl_b64 s[24:25], s[12:13], 2
	s_waitcnt lgkmcnt(0)
	s_add_u32 s24, s4, s24
	s_addc_u32 s25, s5, s25
	s_lshl_b64 s[26:27], s[18:19], 2
	s_add_u32 s26, s2, s26
	s_addc_u32 s27, s3, s27
	s_add_u32 s26, s26, 0x24000000
	s_addc_u32 s27, s27, 0
	s_lshl_b32 s28, s28, 5
	s_and_b32 s36, s28, 0x60
	s_add_i32 m0, s49, 0x18000
	v_lshl_add_u64 v[6:7], v[6:7], 0, s[54:55]
	s_lshl_b32 s30, s1, 13
	s_lshl_b32 s31, s36, 7
	global_load_lds_dwordx4 v[6:7], off
	v_lshl_add_u64 v[4:5], v[4:5], 0, s[54:55]
	s_add_i32 m0, s49, 0x1a000
	s_add_i32 s59, s49, 0x8000
	s_add_i32 s60, s49, 0xa000
	global_load_lds_dwordx4 v[4:5], off
	v_lshl_add_u64 v[0:1], v[0:1], 0, s[54:55]
	s_mov_b32 m0, s59
	s_add_u32 s28, s10, 0x80080
	global_load_lds_dwordx4 v[0:1], off
	v_lshl_add_u64 v[0:1], v[2:3], 0, s[54:55]
	s_mov_b32 m0, s60
	s_addc_u32 s29, s11, 0
	global_load_lds_dwordx4 v[0:1], off
	s_add_i32 m0, s49, 0x1c000
	v_lshl_add_u64 v[0:1], s[28:29], 0, v[176:177]
	global_load_lds_dwordx4 v[0:1], off
	v_lshl_add_u64 v[0:1], s[28:29], 0, v[128:129]
	s_add_i32 m0, s49, 0x1e000
	global_load_lds_dwordx4 v[0:1], off
	s_waitcnt vmcnt(8)
	s_barrier
	s_cmpk_lt_u32 s0, 0x100
	v_lshrrev_b32_e32 v1, 1, v8
	v_and_b32_e32 v1, 24, v1
	v_and_b32_e32 v0, 15, v8
	v_lshlrev_b32_e32 v2, 1, v1
	v_lshl_or_b32 v161, s1, 6, v0
	v_lshl_or_b32 v0, v0, 6, v2
	v_lshlrev_b32_e32 v2, 2, v8
	v_and_b32_e32 v2, 32, v2
	v_bitop3_b32 v3, v0, s30, v2 bitop3:0xde
	v_bitop3_b32 v162, v0, s31, v2 bitop3:0xde
	v_lshlrev_b32_e32 v0, 15, v13
	v_and_b32_e32 v0, 0xffff0000, v0
	v_or_b32_e32 v163, s36, v1
	v_lshl_add_u32 v0, v12, 12, v0
	v_and_b32_e32 v1, 1, v13
	v_lshl_or_b32 v0, v1, 6, v0
	v_lshl_add_u32 v134, v14, 1, v0
	v_lshlrev_b32_e32 v0, 15, v9
	v_and_b32_e32 v0, 0xffff0000, v0
	s_waitcnt vmcnt(6)
	s_cselect_b64 s[28:29], -1, 0
	s_cmp_lg_u64 s[4:5], 0
	v_lshl_add_u32 v0, v10, 12, v0
	v_and_b32_e32 v1, 1, v9
	s_cselect_b64 s[30:31], -1, 0
	s_cmp_lg_u64 s[2:3], 0
	v_lshl_or_b32 v0, v1, 6, v0
	s_cselect_b64 s[34:35], -1, 0
	v_mov_b32_e32 v135, v177
	v_lshl_add_u32 v136, v11, 1, v0
	v_mov_b32_e32 v137, v177
	s_mov_b32 s61, 0
	v_add_u32_e32 v164, 0, v3
	s_barrier
	s_branch .LBB0_303

; #define PG8_STAGE(bufoff, gbase, voff) do { _Pragma("unroll") for (int _i = 0; _i < 2; ++_i) \
;         __builtin_amdgcn_global_load_lds((const unsigned*)((const char*)(gbase) + (voff)[_i]), (LAS unsigned*)(lds + (bufoff) + ldsw + _i * 8192), 16, 0, 0); } while (0)
; #define PG8_WAIT_V(n) asm volatile("s_waitcnt vmcnt(" #n ")" ::: "memory")
; #define PG8_BAR __builtin_amdgcn_s_barrier()
; template <bool F16, class Sched, class Epi>
; __device__ __forceinline__ void gemm_phase(LAS unsigned char* lds, const Gemm g, const Sched& S, const Epi& E, int wave_s) {
;     ...
;     const char* cA = (const char*)g.A + PG8_AOFF(cur); const char* cB = (const char*)g.Bt + (size_t)cur.pn * tstepB;
;     PG8_STAGE(PG8_SB(0, 0), cB, voffB); PG8_STAGE(PG8_SB(0, 1), cB + hstepB, voffB); PG8_STAGE(PG8_SA(0, 0), cA, voffA); PG8_STAGE(PG8_SA(0, 1), cA + hstepA, voffA);
;     if (wr == 1) PG8_BAR;
;     PG8_WAIT_V(2); PG8_BAR;
;     PG8_STAGE(PG8_SB(1, 0), cB + kstep, voffB); PG8_STAGE(PG8_SA(1, 0), cA + kstep, voffA); PG8_STAGE(PG8_SB(1, 1), cB + hstepB + kstep, voffB);
;     PG8_WAIT_V(6); PG8_BAR;
.LBB0_354:
	s_add_u32 s10, s2, 0x1e000000
	s_addc_u32 s11, s3, 0
	s_lshl_b64 s[12:13], s[12:13], 2
	s_add_u32 s12, s14, s12
	s_addc_u32 s13, s15, s13
	s_add_u32 s12, s12, 0x4000
	s_addc_u32 s13, s13, 0
	s_lshl_b64 s[14:15], s[18:19], 2
	s_add_u32 s2, s2, s14
	s_addc_u32 s3, s3, s15
	s_add_u32 s14, s2, 0x24000000
	v_lshrrev_b32_e32 v16, 1, v14
	s_addc_u32 s15, s3, 0
	v_and_b32_e32 v16, 24, v16
	s_lshl_b32 s0, s0, 5
	v_and_b32_e32 v15, 15, v14
	v_lshlrev_b32_e32 v17, 1, v16
	v_lshlrev_b32_e32 v14, 2, v14
	s_and_b32 s2, s0, 0x60
	s_add_i32 m0, s44, 0x18000
	v_lshl_add_u64 v[6:7], v[6:7], 0, s[54:55]
	v_lshl_or_b32 v161, s1, 6, v15
	v_lshl_or_b32 v15, v15, 6, v17
	s_lshl_b32 s1, s1, 13
	v_and_b32_e32 v14, 32, v14
	s_lshl_b32 s0, s2, 7
	global_load_lds_dwordx4 v[6:7], off
	v_lshl_add_u64 v[4:5], v[4:5], 0, s[54:55]
	s_add_i32 m0, s44, 0x1a000
	s_add_i32 s49, s44, 0x8000
	s_add_i32 s52, s44, 0xa000
	v_bitop3_b32 v163, v15, s0, v14 bitop3:0xde
	global_load_lds_dwordx4 v[4:5], off
	v_lshl_add_u64 v[0:1], v[0:1], 0, s[54:55]
	s_mov_b32 m0, s49
	s_add_u32 s0, s4, 0x80080
	v_bitop3_b32 v17, v15, s1, v14 bitop3:0xde
	global_load_lds_dwordx4 v[0:1], off
	v_lshl_add_u64 v[0:1], v[2:3], 0, s[54:55]
	s_mov_b32 m0, s52
	s_addc_u32 s1, s5, 0
	global_load_lds_dwordx4 v[0:1], off
	s_add_i32 m0, s44, 0x1c000
	v_lshl_add_u64 v[0:1], s[0:1], 0, v[176:177]
	global_load_lds_dwordx4 v[0:1], off
	v_lshl_add_u64 v[0:1], s[0:1], 0, v[128:129]
	s_add_i32 m0, s44, 0x1e000
	global_load_lds_dwordx4 v[0:1], off
	s_waitcnt vmcnt(8)
	s_barrier
	s_cmpk_lt_u32 s26, 0x100
	v_lshlrev_b32_e32 v0, 15, v12
	v_and_b32_e32 v0, 0xffff0000, v0
	v_lshl_add_u32 v0, v11, 12, v0
	v_and_b32_e32 v1, 1, v12
	v_lshl_or_b32 v0, v1, 6, v0
	v_lshl_add_u32 v134, v13, 1, v0
	v_lshlrev_b32_e32 v0, 15, v8
	v_and_b32_e32 v0, 0xffff0000, v0
	s_waitcnt vmcnt(6)
	v_lshl_add_u32 v0, v9, 12, v0
	v_and_b32_e32 v1, 1, v8
	v_lshl_or_b32 v0, v1, 6, v0
	s_cselect_b64 s[26:27], -1, 0
	v_or_b32_e32 v165, s2, v16
	v_mov_b32_e32 v135, v177
	v_lshl_add_u32 v136, v10, 1, v0
	v_mov_b32_e32 v137, v177
	s_mov_b32 s53, 0
	v_add_u32_e32 v167, 0, v17
	s_barrier
	s_branch .LBB0_357

; #define PG8_STAGE(bufoff, gbase, voff) do { _Pragma("unroll") for (int _i = 0; _i < 2; ++_i) \
;         __builtin_amdgcn_global_load_lds((const unsigned*)((const char*)(gbase) + (voff)[_i]), (LAS unsigned*)(lds + (bufoff) + ldsw + _i * 8192), 16, 0, 0); } while (0)
; #define PG8_WAIT_V(n) asm volatile("s_waitcnt vmcnt(" #n ")" ::: "memory")
; #define PG8_BAR __builtin_amdgcn_s_barrier()
; template <bool F16, class Sched, class Epi>
; __device__ __forceinline__ void gemm_phase(LAS unsigned char* lds, const Gemm g, const Sched& S, const Epi& E, int wave_s) {
;     ...
;     const char* cA = (const char*)g.A + PG8_AOFF(cur); const char* cB = (const char*)g.Bt + (size_t)cur.pn * tstepB;
;     PG8_STAGE(PG8_SB(0, 0), cB, voffB); PG8_STAGE(PG8_SB(0, 1), cB + hstepB, voffB); PG8_STAGE(PG8_SA(0, 0), cA, voffA); PG8_STAGE(PG8_SA(0, 1), cA + hstepA, voffA);
;     if (wr == 1) PG8_BAR;
;     PG8_WAIT_V(2); PG8_BAR;
;     PG8_STAGE(PG8_SB(1, 0), cB + kstep, voffB); PG8_STAGE(PG8_SA(1, 0), cA + kstep, voffA); PG8_STAGE(PG8_SB(1, 1), cB + hstepB + kstep, voffB);
;     PG8_WAIT_V(6); PG8_BAR;
.LBB0_594:
	s_add_u32 s10, s2, 0x18000000
	s_addc_u32 s11, s3, 0
	s_lshl_b64 s[12:13], s[18:19], 2
	s_add_u32 s2, s2, s12
	s_addc_u32 s3, s3, s13
	s_add_u32 s12, s2, 0x24008000
	s_addc_u32 s13, s3, 0
	v_bfe_u32 v15, v14, 4, 2
	s_lshl_b32 s0, s0, 5
	v_and_b32_e32 v16, 15, v14
	v_lshlrev_b32_e32 v17, 4, v15
	v_lshlrev_b32_e32 v14, 2, v14
	s_and_b32 s24, s0, 0x60
	s_add_i32 m0, s43, 0x18000
	v_lshl_add_u64 v[6:7], v[6:7], 0, s[54:55]
	v_lshl_or_b32 v162, s1, 6, v16
	v_lshl_or_b32 v16, v16, 6, v17
	s_lshl_b32 s1, s1, 13
	v_and_b32_e32 v14, 32, v14
	s_lshl_b32 s0, s24, 7
	global_load_lds_dwordx4 v[6:7], off
	v_lshl_add_u64 v[4:5], v[4:5], 0, s[54:55]
	s_add_i32 m0, s43, 0x1a000
	s_add_i32 s19, s43, 0x8000
	s_add_i32 s47, s43, 0xa000
	v_bitop3_b32 v163, v16, s0, v14 bitop3:0xde
	global_load_lds_dwordx4 v[4:5], off
	v_lshl_add_u64 v[0:1], v[0:1], 0, s[54:55]
	s_mov_b32 m0, s19
	s_add_u32 s0, s6, 0x80080
	v_bitop3_b32 v17, v16, s1, v14 bitop3:0xde
	global_load_lds_dwordx4 v[0:1], off
	v_lshl_add_u64 v[0:1], v[2:3], 0, s[54:55]
	s_mov_b32 m0, s47
	s_addc_u32 s1, s7, 0
	global_load_lds_dwordx4 v[0:1], off
	s_add_i32 m0, s43, 0x1c000
	v_lshl_add_u64 v[0:1], s[0:1], 0, v[176:177]
	global_load_lds_dwordx4 v[0:1], off
	v_lshl_add_u64 v[0:1], s[0:1], 0, v[128:129]
	s_add_i32 m0, s43, 0x1e000
	global_load_lds_dwordx4 v[0:1], off
	s_waitcnt vmcnt(8)
	s_barrier
	s_cmpk_lt_u32 s14, 0x100
	v_lshlrev_b32_e32 v0, 15, v11
	v_and_b32_e32 v0, 0xffff0000, v0
	v_lshl_add_u32 v0, v12, 12, v0
	v_and_b32_e32 v1, 1, v11
	v_lshl_or_b32 v0, v1, 6, v0
	v_lshl_add_u32 v134, v13, 1, v0
	v_lshlrev_b32_e32 v0, 15, v8
	v_and_b32_e32 v0, 0xffff0000, v0
	s_waitcnt vmcnt(6)
	v_lshl_add_u32 v0, v9, 12, v0
	v_and_b32_e32 v1, 1, v8
	v_lshl_or_b32 v0, v1, 6, v0
	s_cselect_b64 s[14:15], -1, 0
	s_mov_b32 s48, 0
	v_cmp_eq_u32_e64 s[2:3], 0, v15
	v_lshl_or_b32 v164, v15, 3, s24
	v_mov_b32_e32 v135, v177
	v_lshl_add_u32 v136, v10, 1, v0
	v_mov_b32_e32 v137, v177
	v_add_u32_e32 v165, 0, v17
	s_barrier
	s_branch .LBB0_597

; #define PG8_STAGE(bufoff, gbase, voff) do { _Pragma("unroll") for (int _i = 0; _i < 2; ++_i) \
;         __builtin_amdgcn_global_load_lds((const unsigned*)((const char*)(gbase) + (voff)[_i]), (LAS unsigned*)(lds + (bufoff) + ldsw + _i * 8192), 16, 0, 0); } while (0)
; #define PG8_WAIT_V(n) asm volatile("s_waitcnt vmcnt(" #n ")" ::: "memory")
; #define PG8_BAR __builtin_amdgcn_s_barrier()
; template <bool F16, class Sched, class Epi>
; __device__ __forceinline__ void gemm_phase(LAS unsigned char* lds, const Gemm g, const Sched& S, const Epi& E, int wave_s) {
;     ...
;     const char* cA = (const char*)g.A + PG8_AOFF(cur); const char* cB = (const char*)g.Bt + (size_t)cur.pn * tstepB;
;     PG8_STAGE(PG8_SB(0, 0), cB, voffB); PG8_STAGE(PG8_SB(0, 1), cB + hstepB, voffB); PG8_STAGE(PG8_SA(0, 0), cA, voffA); PG8_STAGE(PG8_SA(0, 1), cA + hstepA, voffA);
;     if (wr == 1) PG8_BAR;
;     PG8_WAIT_V(2); PG8_BAR;
;     PG8_STAGE(PG8_SB(1, 0), cB + kstep, voffB); PG8_STAGE(PG8_SA(1, 0), cA + kstep, voffA); PG8_STAGE(PG8_SB(1, 1), cB + hstepB + kstep, voffB);
;     PG8_WAIT_V(6); PG8_BAR;
.LBB0_677:
	v_and_b32_e32 v15, 15, v14
	v_lshrrev_b32_e32 v14, 1, v14
	v_and_b32_e32 v14, 24, v14
	s_add_u32 s10, s10, 0x26200000
	v_lshlrev_b32_e32 v16, 1, v14
	s_addc_u32 s11, s11, 0
	v_lshl_or_b32 v148, s0, 6, v15
	v_lshl_or_b32 v16, v15, 6, v16
	v_lshlrev_b32_e32 v15, 2, v15
	s_lshl_b32 s1, s1, 5
	s_lshl_b32 s13, s0, 13
	v_and_b32_e32 v17, 32, v15
	s_and_b32 s1, s1, 0x60
	s_add_i32 m0, s39, 0x18000
	v_lshl_add_u64 v[6:7], v[6:7], 0, s[54:55]
	v_bitop3_b32 v18, v16, s13, v17 bitop3:0xde
	s_lshl_b32 s13, s1, 7
	global_load_lds_dwordx4 v[6:7], off
	v_lshl_add_u64 v[4:5], v[4:5], 0, s[54:55]
	s_add_i32 m0, s39, 0x1a000
	s_add_i32 s46, s39, 0x8000
	s_add_i32 s47, s39, 0xa000
	global_load_lds_dwordx4 v[4:5], off
	v_lshl_add_u64 v[0:1], v[0:1], 0, s[54:55]
	s_mov_b32 m0, s46
	s_add_u32 s14, s2, 0x80080
	global_load_lds_dwordx4 v[0:1], off
	v_lshl_add_u64 v[0:1], v[2:3], 0, s[54:55]
	s_mov_b32 m0, s47
	s_addc_u32 s15, s3, 0
	global_load_lds_dwordx4 v[0:1], off
	s_add_i32 m0, s39, 0x1c000
	v_lshl_add_u64 v[0:1], s[14:15], 0, v[176:177]
	global_load_lds_dwordx4 v[0:1], off
	v_lshl_add_u64 v[0:1], s[14:15], 0, v[128:129]
	s_add_i32 m0, s39, 0x1e000
	global_load_lds_dwordx4 v[0:1], off
	s_waitcnt vmcnt(8)
	s_barrier
	s_cmpk_lt_u32 s12, 0x100
	v_lshlrev_b32_e32 v0, 15, v12
	v_and_b32_e32 v0, 0xffff0000, v0
	v_lshl_add_u32 v0, v11, 12, v0
	v_and_b32_e32 v1, 1, v12
	v_lshl_or_b32 v0, v1, 6, v0
	v_lshl_add_u32 v134, v13, 1, v0
	v_lshlrev_b32_e32 v0, 15, v8
	v_bitop3_b32 v149, v16, s13, v17 bitop3:0xde
	s_cselect_b64 s[12:13], -1, 0
	s_lshl_b32 s0, s0, 8
	v_and_b32_e32 v0, 0xffff0000, v0
	s_waitcnt vmcnt(6)
	s_add_i32 s0, s0, 0
	v_lshl_add_u32 v0, v9, 12, v0
	v_and_b32_e32 v1, 1, v8
	s_add_i32 s0, s0, 0x20000
	v_lshl_or_b32 v0, v1, 6, v0
	v_add_u32_e32 v150, s0, v15
	v_or_b32_e32 v151, s1, v14
	v_mov_b32_e32 v135, v177
	v_lshl_add_u32 v136, v10, 1, v0
	v_mov_b32_e32 v137, v177
	s_mov_b32 s48, 0
	v_add_u32_e32 v152, 0, v18
	s_barrier
	s_branch .LBB0_680

; #define PG8_STAGE(bufoff, gbase, voff) do { _Pragma("unroll") for (int _i = 0; _i < 2; ++_i) \
;         __builtin_amdgcn_global_load_lds((const unsigned*)((const char*)(gbase) + (voff)[_i]), (LAS unsigned*)(lds + (bufoff) + ldsw + _i * 8192), 16, 0, 0); } while (0)
; #define PG8_WAIT_V(n) asm volatile("s_waitcnt vmcnt(" #n ")" ::: "memory")
; #define PG8_BAR __builtin_amdgcn_s_barrier()
; template <bool F16, class Sched, class Epi>
; __device__ __forceinline__ void gemm_phase(LAS unsigned char* lds, const Gemm g, const Sched& S, const Epi& E, int wave_s) {
;     ...
;     const char* cA = (const char*)g.A + PG8_AOFF(cur); const char* cB = (const char*)g.Bt + (size_t)cur.pn * tstepB;
;     PG8_STAGE(PG8_SB(0, 0), cB, voffB); PG8_STAGE(PG8_SB(0, 1), cB + hstepB, voffB); PG8_STAGE(PG8_SA(0, 0), cA, voffA); PG8_STAGE(PG8_SA(0, 1), cA + hstepA, voffA);
;     if (wr == 1) PG8_BAR;
;     PG8_WAIT_V(2); PG8_BAR;
;     PG8_STAGE(PG8_SB(1, 0), cB + kstep, voffB); PG8_STAGE(PG8_SA(1, 0), cA + kstep, voffA); PG8_STAGE(PG8_SB(1, 1), cB + hstepB + kstep, voffB);
;     PG8_WAIT_V(6); PG8_BAR;
.LBB0_691:
	v_lshrrev_b32_e32 v10, 1, v8
	v_and_b32_e32 v10, 24, v10
	s_add_u32 s8, s8, 0x22000000
	v_and_b32_e32 v9, 15, v8
	v_lshlrev_b32_e32 v11, 1, v10
	v_lshlrev_b32_e32 v8, 2, v8
	s_addc_u32 s9, s9, 0
	v_lshl_or_b32 v136, s13, 6, v9
	v_lshl_or_b32 v9, v9, 6, v11
	s_lshl_b32 s13, s13, 13
	v_and_b32_e32 v8, 32, v8
	s_lshl_b32 s11, s11, 5
	v_bitop3_b32 v11, v9, s13, v8 bitop3:0xde
	s_and_b32 s13, s11, 0x60
	s_add_i32 m0, s41, 0x18000
	v_lshl_add_u64 v[6:7], v[6:7], 0, s[54:55]
	s_lshl_b32 s11, s13, 7
	global_load_lds_dwordx4 v[6:7], off
	v_lshl_add_u64 v[4:5], v[4:5], 0, s[54:55]
	s_add_i32 m0, s41, 0x1a000
	s_add_i32 s45, s41, 0x8000
	s_add_i32 s46, s41, 0xa000
	global_load_lds_dwordx4 v[4:5], off
	v_lshl_add_u64 v[0:1], v[0:1], 0, s[54:55]
	s_mov_b32 m0, s45
	s_add_u32 s14, s2, 0x10080
	global_load_lds_dwordx4 v[0:1], off
	v_lshl_add_u64 v[0:1], v[2:3], 0, s[54:55]
	s_mov_b32 m0, s46
	s_addc_u32 s15, s3, 0
	global_load_lds_dwordx4 v[0:1], off
	s_add_i32 m0, s41, 0x1c000
	v_lshl_add_u64 v[0:1], s[14:15], 0, v[176:177]
	global_load_lds_dwordx4 v[0:1], off
	v_lshl_add_u64 v[0:1], s[14:15], 0, v[128:129]
	s_add_i32 m0, s41, 0x1e000
	global_load_lds_dwordx4 v[0:1], off
	s_waitcnt vmcnt(8)
	s_barrier
	s_cmpk_lt_u32 s10, 0x100
	s_waitcnt vmcnt(6)
	v_bitop3_b32 v137, v9, s11, v8 bitop3:0xde
	s_cselect_b64 s[10:11], -1, 0
	v_or_b32_e32 v138, s13, v10
	s_cmp_eq_u32 s20, 3
	s_cselect_b32 s32, s87, 32
	s_add_i32 s47, s32, s12
	v_add_u32_e32 v139, 0, v11
	s_barrier
	s_branch .LBB0_694

; #define PG8_STAGE(bufoff, gbase, voff) do { _Pragma("unroll") for (int _i = 0; _i < 2; ++_i) \
;         __builtin_amdgcn_global_load_lds((const unsigned*)((const char*)(gbase) + (voff)[_i]), (LAS unsigned*)(lds + (bufoff) + ldsw + _i * 8192), 16, 0, 0); } while (0)
; #define PG8_WAIT_V(n) asm volatile("s_waitcnt vmcnt(" #n ")" ::: "memory")
; #define PG8_BAR __builtin_amdgcn_s_barrier()
; template <bool F16, class Sched, class Epi>
; __device__ __forceinline__ void gemm_phase(LAS unsigned char* lds, const Gemm g, const Sched& S, const Epi& E, int wave_s) {
;     ...
;     const char* cA = (const char*)g.A + PG8_AOFF(cur); const char* cB = (const char*)g.Bt + (size_t)cur.pn * tstepB;
;     PG8_STAGE(PG8_SB(0, 0), cB, voffB); PG8_STAGE(PG8_SB(0, 1), cB + hstepB, voffB); PG8_STAGE(PG8_SA(0, 0), cA, voffA); PG8_STAGE(PG8_SA(0, 1), cA + hstepA, voffA);
;     if (wr == 1) PG8_BAR;
;     PG8_WAIT_V(2); PG8_BAR;
;     PG8_STAGE(PG8_SB(1, 0), cB + kstep, voffB); PG8_STAGE(PG8_SA(1, 0), cA + kstep, voffA); PG8_STAGE(PG8_SB(1, 1), cB + hstepB + kstep, voffB);
;     PG8_WAIT_V(6); PG8_BAR;
.LBB0_786:
	s_add_u32 s8, s4, s19
	s_addc_u32 s9, s5, 0
	s_lshl_b64 s[10:11], s[50:51], 2
	s_add_u32 s4, s4, s10
	s_addc_u32 s5, s5, s11
	s_add_u32 s10, s4, 0x24000000
	s_addc_u32 s11, s5, 0
	v_bfe_u32 v17, v15, 4, 2
	s_lshl_b32 s0, s0, 5
	v_and_b32_e32 v18, 15, v15
	v_lshlrev_b32_e32 v19, 4, v17
	v_lshlrev_b32_e32 v15, 2, v15
	s_and_b32 s14, s0, 0x60
	s_add_i32 m0, s46, 0x18000
	v_lshl_add_u64 v[6:7], v[6:7], 0, s[54:55]
	v_lshl_or_b32 v162, s1, 6, v18
	v_lshl_or_b32 v18, v18, 6, v19
	s_lshl_b32 s1, s1, 13
	v_and_b32_e32 v15, 32, v15
	s_lshl_b32 s0, s14, 7
	global_load_lds_dwordx4 v[6:7], off
	v_lshl_add_u64 v[4:5], v[4:5], 0, s[54:55]
	s_add_i32 m0, s46, 0x1a000
	s_add_i32 s52, s46, 0x8000
	s_add_i32 s53, s46, 0xa000
	v_bitop3_b32 v163, v18, s0, v15 bitop3:0xde
	global_load_lds_dwordx4 v[4:5], off
	v_lshl_add_u64 v[0:1], v[0:1], 0, s[54:55]
	s_mov_b32 m0, s52
	s_add_u32 s0, s30, 0x160080
	v_bitop3_b32 v19, v18, s1, v15 bitop3:0xde
	global_load_lds_dwordx4 v[0:1], off
	v_lshl_add_u64 v[0:1], v[2:3], 0, s[54:55]
	s_mov_b32 m0, s53
	s_addc_u32 s1, s31, 0
	global_load_lds_dwordx4 v[0:1], off
	s_add_i32 m0, s46, 0x1c000
	v_lshl_add_u64 v[0:1], s[0:1], 0, v[176:177]
	global_load_lds_dwordx4 v[0:1], off
	v_lshl_add_u64 v[0:1], s[0:1], 0, v[128:129]
	s_add_i32 m0, s46, 0x1e000
	s_mov_b64 s[24:25], 0x160080
	global_load_lds_dwordx4 v[0:1], off
	s_waitcnt vmcnt(8)
	s_barrier
	v_lshrrev_b32_e32 v1, 1, v13
	v_mul_lo_u32 v0, v12, s92
	v_mad_u64_u32 v[0:1], s[0:1], v1, s15, v[0:1]
	v_or_b32_e32 v0, v0, v14
	v_add_lshl_u32 v0, v0, v16, 1
	v_mov_b32_e32 v1, v177
	v_lshl_add_u64 v[134:135], v[0:1], 0, s[24:25]
	v_lshrrev_b32_e32 v1, 1, v8
	v_mul_lo_u32 v0, v9, s92
	v_mad_u64_u32 v[0:1], s[0:1], v1, s15, v[0:1]
	s_waitcnt vmcnt(6)
	v_or_b32_e32 v0, v0, v10
	s_cmpk_lt_u32 s12, 0x100
	v_add_lshl_u32 v0, v0, v11, 1
	v_mov_b32_e32 v1, v177
	s_cselect_b64 s[12:13], -1, 0
	s_mov_b32 s58, 0
	v_cmp_eq_u32_e64 s[4:5], 0, v17
	v_lshl_or_b32 v164, v17, 3, s14
	v_lshl_add_u64 v[136:137], v[0:1], 0, s[24:25]
	v_add_u32_e32 v165, 0, v19
	s_barrier
	s_branch .LBB0_789

; #define PG8_STAGE(bufoff, gbase, voff) do { _Pragma("unroll") for (int _i = 0; _i < 2; ++_i) \
;         __builtin_amdgcn_global_load_lds((const unsigned*)((const char*)(gbase) + (voff)[_i]), (LAS unsigned*)(lds + (bufoff) + ldsw + _i * 8192), 16, 0, 0); } while (0)
; #define PG8_WAIT_V(n) asm volatile("s_waitcnt vmcnt(" #n ")" ::: "memory")
; #define PG8_BAR __builtin_amdgcn_s_barrier()
; template <bool F16, class Sched, class Epi>
; __device__ __forceinline__ void gemm_phase(LAS unsigned char* lds, const Gemm g, const Sched& S, const Epi& E, int wave_s) {
;     ...
;     const char* cA = (const char*)g.A + PG8_AOFF(cur); const char* cB = (const char*)g.Bt + (size_t)cur.pn * tstepB;
;     PG8_STAGE(PG8_SB(0, 0), cB, voffB); PG8_STAGE(PG8_SB(0, 1), cB + hstepB, voffB); PG8_STAGE(PG8_SA(0, 0), cA, voffA); PG8_STAGE(PG8_SA(0, 1), cA + hstepA, voffA);
;     if (wr == 1) PG8_BAR;
;     PG8_WAIT_V(2); PG8_BAR;
;     PG8_STAGE(PG8_SB(1, 0), cB + kstep, voffB); PG8_STAGE(PG8_SA(1, 0), cA + kstep, voffA); PG8_STAGE(PG8_SB(1, 1), cB + hstepB + kstep, voffB);
;     PG8_WAIT_V(6); PG8_BAR;
.LBB0_865:
	s_and_b64 s[14:15], s[22:23], exec
	s_brev_b32 s14, 24
	s_cselect_b32 s14, 0x24100000, s14
	s_add_u32 s14, s2, s14
	s_addc_u32 s15, s3, 0
	s_add_u32 s22, s2, 0x22000000
	s_addc_u32 s23, s3, 0
	s_lshl_b32 s20, s20, 11
	s_mov_b32 s21, s51
	s_lshl_b64 s[20:21], s[20:21], 2
	s_waitcnt lgkmcnt(0)
	s_add_u32 s20, s4, s20
	s_addc_u32 s21, s5, s21
	s_lshl_b64 s[4:5], s[50:51], 2
	s_add_u32 s4, s2, s4
	s_addc_u32 s5, s3, s5
	s_add_u32 s24, s4, 0x24000000
	s_mov_b32 s19, s51
	s_addc_u32 s25, s5, 0
	s_lshl_b64 s[4:5], s[18:19], 2
	s_add_u32 s2, s2, s4
	s_addc_u32 s3, s3, s5
	s_add_u32 s18, s2, 0x24018000
	v_bfe_u32 v16, v8, 4, 2
	s_addc_u32 s19, s3, 0
	v_and_b32_e32 v15, 15, v8
	v_lshlrev_b32_e32 v17, 4, v16
	v_lshlrev_b32_e32 v8, 2, v8
	s_lshl_b32 s1, s1, 5
	v_lshl_or_b32 v207, s26, 6, v15
	v_lshl_or_b32 v15, v15, 6, v17
	s_lshl_b32 s2, s26, 13
	v_and_b32_e32 v8, 32, v8
	s_and_b32 s1, s1, 0x60
	s_add_i32 m0, s44, 0x18000
	v_lshl_add_u64 v[6:7], v[6:7], 0, s[54:55]
	v_bitop3_b32 v17, v15, s2, v8 bitop3:0xde
	s_lshl_b32 s2, s1, 7
	global_load_lds_dwordx4 v[6:7], off
	v_lshl_add_u64 v[4:5], v[4:5], 0, s[54:55]
	s_add_i32 m0, s44, 0x1a000
	s_add_i32 s49, s44, 0x8000
	s_add_i32 s52, s44, 0xa000
	v_bitop3_b32 v208, v15, s2, v8 bitop3:0xde
	global_load_lds_dwordx4 v[4:5], off
	v_lshl_add_u64 v[0:1], v[0:1], 0, s[54:55]
	s_mov_b32 m0, s49
	s_add_u32 s2, s12, 0x80080
	global_load_lds_dwordx4 v[0:1], off
	v_lshl_add_u64 v[0:1], v[2:3], 0, s[54:55]
	s_mov_b32 m0, s52
	s_addc_u32 s3, s13, 0
	global_load_lds_dwordx4 v[0:1], off
	s_add_i32 m0, s44, 0x1c000
	v_lshl_add_u64 v[0:1], s[2:3], 0, v[176:177]
	global_load_lds_dwordx4 v[0:1], off
	v_lshl_add_u64 v[0:1], s[2:3], 0, v[178:179]
	s_add_i32 m0, s44, 0x1e000
	global_load_lds_dwordx4 v[0:1], off
	s_waitcnt vmcnt(8)
	s_barrier
	s_cmpk_lt_u32 s0, 0x100
	v_lshlrev_b32_e32 v0, 15, v13
	v_and_b32_e32 v0, 0xffff0000, v0
	v_lshl_add_u32 v0, v12, 12, v0
	v_and_b32_e32 v1, 1, v13
	v_lshl_or_b32 v0, v1, 6, v0
	v_lshl_add_u32 v184, v14, 1, v0
	v_lshlrev_b32_e32 v0, 15, v9
	v_and_b32_e32 v0, 0xffff0000, v0
	s_waitcnt vmcnt(6)
	v_lshl_add_u32 v0, v10, 12, v0
	v_and_b32_e32 v1, 1, v9
	v_lshl_or_b32 v0, v1, 6, v0
	s_mov_b32 s48, 0
	s_cselect_b64 s[26:27], -1, 0
	v_cmp_eq_u32_e64 s[2:3], 0, v16
	v_lshl_or_b32 v209, v16, 3, s1
	v_mov_b32_e32 v185, v177
	v_lshl_add_u32 v186, v11, 1, v0
	v_mov_b32_e32 v187, v177
	v_add_u32_e32 v210, 0, v17
	s_barrier
	s_branch .LBB0_868

;     __device__ void init(int M, int N, int G_, int c_) { asm volatile("" : "+s"(c_)); nM = M / BM; nN = N / BM; nwg = nM * nN; G = G_; c = c_; }
;     __device__ void init(int mode_, int nOther, int G_, int c_, int grp) { asm volatile("" : "+s"(c_)); mode = mode_; nwg = 4 * nOther; G = G_; c = c_; p0 = 4 * grp; }
; #define PG8_STAGE(bufoff, gbase, voff) do { _Pragma("unroll") for (int _i = 0; _i < 2; ++_i) \
;         __builtin_amdgcn_global_load_lds((const unsigned*)((const char*)(gbase) + (voff)[_i]), (LAS unsigned*)(lds + (bufoff) + ldsw + _i * 8192), 16, 0, 0); } while (0)
; #define PG8_WAIT_V(n) asm volatile("s_waitcnt vmcnt(" #n ")" ::: "memory")
; #define PG8_BAR __builtin_amdgcn_s_barrier()
; __device__ __forceinline__ unsigned xb_xcc_id() { unsigned r; asm volatile("s_getreg_b32 %0, hwreg(20, 0, 4)" : "=s"(r)); return r & 0xFu; }
; #define XBCUR WSP((i & 1) ? WS_H2 : WS_H)
; #define GRP (blk_now() & 7)
; #define GC (blk_now() >> 3)
; template <bool F16, class Sched, class Epi>
; __device__ __forceinline__ void gemm_phase(LAS unsigned char* lds, const Gemm g, const Sched& S, const Epi& E, int wave_s) {
;     ...
;     const char* cA = (const char*)g.A + PG8_AOFF(cur); const char* cB = (const char*)g.Bt + (size_t)cur.pn * tstepB;
;     PG8_STAGE(PG8_SB(0, 0), cB, voffB); PG8_STAGE(PG8_SB(0, 1), cB + hstepB, voffB); PG8_STAGE(PG8_SA(0, 0), cA, voffA); PG8_STAGE(PG8_SA(0, 1), cA + hstepA, voffA);
;     if (wr == 1) PG8_BAR;
;     PG8_WAIT_V(2); PG8_BAR;
;     PG8_STAGE(PG8_SB(1, 0), cB + kstep, voffB); PG8_STAGE(PG8_SA(1, 0), cA + kstep, voffA); PG8_STAGE(PG8_SB(1, 1), cB + hstepB + kstep, voffB);
;     PG8_WAIT_V(6); PG8_BAR;
; __global__ void __launch_bounds__(NWAVES * 64, 2) fwd_megakernel(Args args_unused) {
;     ...
;             pg8::GroupOrder S; S.init(0, D / 256, GS, GC, GRP);
;             pg8::Gemm g{XBCUR, WSP(WS_WPG) + (size_t)i * D * D, NTOK, D, D, D, 0, 0};
;             XcdBarrier gb; gb.bar = (unsigned*)(A->ws + WS_BAR) + 4096 * GRP; gb.x = xb_xcc_id(); gb.st = bar_st; gb.G = (unsigned)GS;
;             EpiPleFinal E{pg8::EpiPle{XBCUR, nullptr, WSP(WS_PP), A->in[16] + i * D, SSQ(3 * i + 2), SSQ(3 * i + 3)}, A->in[18], A->out, gb, wave_s};
;             pg8::gemm_phase<true>(lds, g, S, E, wave_s);
.LBB0_989:
	s_lshl_b32 s4, s22, 14
	s_and_b32 s4, s4, 0x1c000
	s_add_u32 s4, s2, s4
	s_addc_u32 s5, s3, 0
	s_add_u32 s78, s4, 0x26100000
	s_addc_u32 s79, s5, 0
	s_and_b32 s9, s9, 15
	s_add_u32 s80, s2, 0x22000000
	s_addc_u32 s81, s3, 0
	s_waitcnt lgkmcnt(0)
	s_add_u32 s82, s0, 0x6000
	s_addc_u32 s83, s1, 0
	s_lshl_b64 s[0:1], s[50:51], 2
	s_add_u32 s0, s2, s0
	s_addc_u32 s1, s3, s1
	s_add_u32 s84, s0, 0x24000000
	s_addc_u32 s85, s1, 0
	s_add_u32 s86, s2, 0x24060000
	s_addc_u32 s87, s3, 0
	s_lshl_b32 s0, s7, 5
	s_and_b32 s7, s0, 0x60
	s_add_i32 m0, s18, 0x18000
	v_lshl_add_u64 v[6:7], v[6:7], 0, s[54:55]
	s_lshl_b32 s2, s8, 13
	s_lshl_b32 s3, s7, 7
	global_load_lds_dwordx4 v[6:7], off
	v_lshl_add_u64 v[4:5], v[4:5], 0, s[54:55]
	s_add_i32 m0, s18, 0x1a000
	s_add_i32 s50, s18, 0x8000
	s_add_i32 s22, s18, 0xa000
	global_load_lds_dwordx4 v[4:5], off
	v_lshl_add_u64 v[0:1], v[0:1], 0, s[54:55]
	s_mov_b32 m0, s50
	s_add_u32 s0, s72, 0x80080
	global_load_lds_dwordx4 v[0:1], off
	v_lshl_add_u64 v[0:1], v[2:3], 0, s[54:55]
	s_mov_b32 m0, s22
	s_addc_u32 s1, s73, 0
	global_load_lds_dwordx4 v[0:1], off
	s_add_i32 m0, s18, 0x1c000
	v_lshl_add_u64 v[0:1], s[0:1], 0, v[176:177]
	global_load_lds_dwordx4 v[0:1], off
	v_lshl_add_u64 v[0:1], s[0:1], 0, v[178:179]
	s_add_i32 m0, s18, 0x1e000
	global_load_lds_dwordx4 v[0:1], off
	s_waitcnt vmcnt(8)
	s_barrier
	s_cmpk_lt_u32 s6, 0x100
	s_cselect_b64 s[88:89], -1, 0
	s_add_u32 s90, s4, 0x26100200
	s_addc_u32 s91, s5, 0
	s_add_u32 s92, s4, 0x26101000
	s_addc_u32 s93, s5, 0
	s_add_u32 s94, s4, 0x26101100
	s_addc_u32 s95, s5, 0
	s_add_u32 s96, s4, 0x26101200
	s_addc_u32 s97, s5, 0
	s_add_u32 s68, s4, 0x26101300
	s_addc_u32 s69, s5, 0
	s_cmp_eq_u32 s9, 15
	s_cselect_b64 s[0:1], -1, 0
	v_writelane_b32 v255, s0, 29
	s_cmp_eq_u32 s9, 14
	v_bfe_u32 v16, v12, 4, 2
	v_writelane_b32 v255, s1, 30
	s_cselect_b64 s[0:1], -1, 0
	v_writelane_b32 v255, s0, 31
	s_cmp_eq_u32 s9, 13
	v_and_b32_e32 v15, 15, v12
	v_writelane_b32 v255, s1, 32
	s_cselect_b64 s[0:1], -1, 0
	v_writelane_b32 v255, s0, 33
	s_cmp_eq_u32 s9, 12
	v_lshlrev_b32_e32 v17, 4, v16
	v_writelane_b32 v255, s1, 34
	s_cselect_b64 s[0:1], -1, 0
	v_writelane_b32 v255, s0, 35
	s_cmp_eq_u32 s9, 11
	v_lshlrev_b32_e32 v0, 2, v12
	v_writelane_b32 v255, s1, 36
	s_cselect_b64 s[0:1], -1, 0
	v_writelane_b32 v255, s0, 37
	s_cmp_eq_u32 s9, 10
	v_lshl_or_b32 v207, s8, 6, v15
	v_writelane_b32 v255, s1, 38
	s_cselect_b64 s[0:1], -1, 0
	v_writelane_b32 v255, s0, 39
	s_cmp_eq_u32 s9, 9
	v_lshl_or_b32 v15, v15, 6, v17
	v_writelane_b32 v255, s1, 40
	s_cselect_b64 s[0:1], -1, 0
	v_writelane_b32 v255, s0, 41
	s_cmp_eq_u32 s9, 8
	v_and_b32_e32 v0, 32, v0
	v_writelane_b32 v255, s1, 42
	s_cselect_b64 s[0:1], -1, 0
	v_writelane_b32 v255, s0, 43
	s_cmp_eq_u32 s9, 7
	v_bitop3_b32 v1, v15, s2, v0 bitop3:0xde
	v_writelane_b32 v255, s1, 44
	s_cselect_b64 s[0:1], -1, 0
	v_writelane_b32 v255, s0, 45
	s_cmp_eq_u32 s9, 6
	v_bitop3_b32 v208, v15, s3, v0 bitop3:0xde
	v_writelane_b32 v255, s1, 46
	s_cselect_b64 s[0:1], -1, 0
	v_writelane_b32 v255, s0, 47
	s_cmp_eq_u32 s9, 5
	v_lshlrev_b32_e32 v0, 15, v13
	v_writelane_b32 v255, s1, 48
	s_cselect_b64 s[0:1], -1, 0
	v_writelane_b32 v255, s0, 49
	s_cmp_eq_u32 s9, 4
	v_and_b32_e32 v0, 0xffff0000, v0
	v_writelane_b32 v255, s1, 50
	s_cselect_b64 s[0:1], -1, 0
	s_cmp_eq_u32 s9, 3
	s_cselect_b64 s[28:29], -1, 0
	s_cmp_eq_u32 s9, 2
	s_cselect_b64 s[30:31], -1, 0
	s_cmp_eq_u32 s9, 1
	v_writelane_b32 v255, s0, 51
	s_cselect_b64 s[34:35], -1, 0
	s_cmp_eq_u32 s9, 0
	v_writelane_b32 v255, s1, 52
	s_cselect_b64 s[36:37], -1, 0
	s_lshl_b32 s0, s9, 8
	s_add_u32 s0, s78, s0
	s_addc_u32 s1, s79, 0
	s_add_u32 s48, s0, 0x1400
	s_addc_u32 s49, s1, 0
	v_lshl_add_u32 v0, v11, 12, v0
	v_and_b32_e32 v2, 1, v13
	s_add_u32 s52, s0, 0x2400
	v_lshl_or_b32 v0, v2, 6, v0
	s_addc_u32 s53, s1, 0
	v_lshl_add_u32 v184, v14, 1, v0
	v_lshlrev_b32_e32 v0, 15, v8
	s_add_u32 s58, s4, 0x26103400
	v_and_b32_e32 v0, 0xffff0000, v0
	s_waitcnt vmcnt(6)
	s_addc_u32 s59, s5, 0
	v_lshl_add_u32 v0, v9, 12, v0
	v_and_b32_e32 v2, 1, v8
	s_add_u32 s60, s4, 0x26103500
	v_lshl_or_b32 v0, v2, 6, v0
	s_mov_b32 s23, 0
	v_cmp_eq_u32_e64 s[2:3], 0, v16
	s_addc_u32 s61, s5, 0
	v_lshl_or_b32 v209, v16, 3, s7
	v_mov_b32_e32 v185, v177
	v_lshl_add_u32 v186, v10, 1, v0
	v_mov_b32_e32 v187, v177
	v_add_u32_e32 v210, 0, v1
	s_barrier
	s_branch .LBB0_992
